# sample-row GEMMs (scan phase critical path and LN phase): first K iteration peeled with srcC = 0, no accumulator zeroing
# speedup vs baseline: 1.0002x; 1.0002x over previous
.LBB0_744:
	s_ashr_i32 s97, s96, 31
	s_lshl_b64 s[4:5], s[96:97], 19
	v_readlane_b32 s8, v253, 5
	s_add_u32 s82, s8, s4
	v_readlane_b32 s4, v253, 6
	s_addc_u32 s83, s4, s5
	s_and_b64 s[4:5], s[80:81], exec
	s_cselect_b32 s11, s83, s1
	s_cselect_b32 s13, s82, s0
	s_ashr_i32 s95, s94, 31
	s_lshl_b64 s[4:5], s[94:95], 19
	v_readlane_b32 s8, v253, 61
	s_add_u32 s4, s8, s4
	v_readlane_b32 s8, v253, 62
	s_addc_u32 s5, s8, s5
	s_and_b64 s[8:9], s[80:81], exec
	s_cselect_b32 s14, s5, s7
	s_cselect_b32 s15, s4, s6
	s_add_u32 s0, s0, 0x40080
	s_addc_u32 s1, s1, 0
	s_add_u32 s16, s6, 0x100
	s_addc_u32 s17, s7, 0
	s_mov_b32 s18, -2
	s_add_u32 s6, s0, 0xfffc0080
	s_addc_u32 s7, s1, -1
	s_add_i32 s19, 0, 0x10000
	s_cmp_eq_u32 s18, 12
	s_cselect_b32 s9, s11, s7
	s_cselect_b32 s8, s13, s6
	v_add_u32_e32 v0, s19, v198
	s_cselect_b32 s7, s14, s17
	s_cselect_b32 s6, s15, s16
	s_add_i32 s25, 0, 0x14000
	ds_read_b128 v[18:21], v0
	ds_read_b128 v[22:25], v0 offset:1024
	ds_read_b128 v[34:37], v0 offset:2048
	ds_read_b128 v[38:41], v0 offset:3072
	v_add_u32_e32 v0, s25, v198
	ds_read_b128 v[146:149], v0
	ds_read_b128 v[150:153], v0 offset:1024
	ds_read_b128 v[172:175], v0 offset:2048
	ds_read_b128 v[176:179], v0 offset:3072
	v_lshl_add_u64 v[188:189], s[0:1], 0, v[168:169]
	s_add_i32 m0, s87, 0xc000
	ds_read_b128 v[180:183], v200
	ds_read_b128 v[184:187], v200 offset:1024
	ds_read_b128 v[202:205], v200 offset:2048
	ds_read_b128 v[206:209], v200 offset:3072
	ds_read_b128 v[210:213], v200 offset:4096
	ds_read_b128 v[214:217], v200 offset:5120
	ds_read_b128 v[218:221], v200 offset:6144
	ds_read_b128 v[234:237], v200 offset:7168
	global_load_lds_dwordx4 v[188:189], off
	v_lshl_add_u64 v[188:189], s[0:1], 0, v[170:171]
	s_add_i32 m0, s87, 0xe000
	s_nop 0
	global_load_lds_dwordx4 v[188:189], off
	s_waitcnt vmcnt(8)
	s_waitcnt lgkmcnt(0)
	s_barrier
	s_setprio 1
	s_waitcnt lgkmcnt(0)
	v_mfma_f32_16x16x32_bf16 v[142:145], v[18:21], v[180:183], 0
	v_mfma_f32_16x16x32_bf16 v[138:141], v[34:37], v[180:183], 0
	v_mfma_f32_16x16x32_bf16 v[126:129], v[18:21], v[202:205], 0
	v_mfma_f32_16x16x32_bf16 v[122:125], v[34:37], v[202:205], 0
	v_mfma_f32_16x16x32_bf16 v[110:113], v[18:21], v[210:213], 0
	v_mfma_f32_16x16x32_bf16 v[106:109], v[34:37], v[210:213], 0
	v_mfma_f32_16x16x32_bf16 v[94:97], v[18:21], v[218:221], 0
	v_mfma_f32_16x16x32_bf16 v[90:93], v[34:37], v[218:221], 0
	v_mfma_f32_16x16x32_bf16 v[142:145], v[22:25], v[184:187], v[142:145]
	v_mfma_f32_16x16x32_bf16 v[138:141], v[38:41], v[184:187], v[138:141]
	v_mfma_f32_16x16x32_bf16 v[126:129], v[22:25], v[206:209], v[126:129]
	v_mfma_f32_16x16x32_bf16 v[122:125], v[38:41], v[206:209], v[122:125]
	v_mfma_f32_16x16x32_bf16 v[110:113], v[22:25], v[214:217], v[110:113]
	v_mfma_f32_16x16x32_bf16 v[106:109], v[38:41], v[214:217], v[106:109]
	v_mfma_f32_16x16x32_bf16 v[94:97], v[22:25], v[234:237], v[94:97]
	v_mfma_f32_16x16x32_bf16 v[90:93], v[38:41], v[234:237], v[90:93]
	s_setprio 0
	s_setprio 1
	v_mfma_f32_16x16x32_bf16 v[134:137], v[146:149], v[180:183], 0
	v_mfma_f32_16x16x32_bf16 v[130:133], v[172:175], v[180:183], 0
	v_mfma_f32_16x16x32_bf16 v[118:121], v[146:149], v[202:205], 0
	v_mfma_f32_16x16x32_bf16 v[114:117], v[172:175], v[202:205], 0
	v_mfma_f32_16x16x32_bf16 v[102:105], v[146:149], v[210:213], 0
	v_mfma_f32_16x16x32_bf16 v[98:101], v[172:175], v[210:213], 0
	v_mfma_f32_16x16x32_bf16 v[86:89], v[146:149], v[218:221], 0
	v_mfma_f32_16x16x32_bf16 v[82:85], v[172:175], v[218:221], 0
	v_mfma_f32_16x16x32_bf16 v[134:137], v[150:153], v[184:187], v[134:137]
	v_mfma_f32_16x16x32_bf16 v[130:133], v[176:179], v[184:187], v[130:133]
	v_mfma_f32_16x16x32_bf16 v[118:121], v[150:153], v[206:209], v[118:121]
	v_mfma_f32_16x16x32_bf16 v[114:117], v[176:179], v[206:209], v[114:117]
	v_mfma_f32_16x16x32_bf16 v[102:105], v[150:153], v[214:217], v[102:105]
	v_mfma_f32_16x16x32_bf16 v[98:101], v[176:179], v[214:217], v[98:101]
	v_mfma_f32_16x16x32_bf16 v[86:89], v[150:153], v[234:237], v[86:89]
	v_mfma_f32_16x16x32_bf16 v[82:85], v[176:179], v[234:237], v[82:85]
	s_setprio 0
	s_barrier
	s_add_i32 s19, s19, s69
	v_lshl_add_u64 v[188:189], s[6:7], 0, v[156:157]
	s_mov_b32 m0, s19
	ds_read_b128 v[180:183], v200 offset:16384
	ds_read_b128 v[184:187], v200 offset:17408
	ds_read_b128 v[202:205], v200 offset:18432
	ds_read_b128 v[206:209], v200 offset:19456
	ds_read_b128 v[210:213], v200 offset:20480
	ds_read_b128 v[214:217], v200 offset:21504
	ds_read_b128 v[218:221], v200 offset:22528
	ds_read_b128 v[234:237], v200 offset:23552
	global_load_lds_dwordx4 v[188:189], off
	s_add_i32 m0, s19, 0x2000
	s_add_u32 s20, s6, 0x40000
	v_lshl_add_u64 v[222:223], s[6:7], 0, v[160:161]
	s_addc_u32 s21, s7, 0
	s_add_i32 s19, s25, s69
	global_load_lds_dwordx4 v[222:223], off
	v_lshl_add_u64 v[238:239], s[20:21], 0, v[156:157]
	s_mov_b32 m0, s19
	v_lshl_add_u64 v[240:241], s[8:9], 0, v[158:159]
	global_load_lds_dwordx4 v[238:239], off
	v_lshl_add_u64 v[238:239], s[20:21], 0, v[160:161]
	s_add_i32 m0, s19, 0x2000
	s_nop 0
	global_load_lds_dwordx4 v[238:239], off
	v_lshl_add_u64 v[238:239], s[8:9], 0, v[154:155]
	s_mov_b32 m0, s87
	s_nop 0
	global_load_lds_dwordx4 v[238:239], off
	s_mov_b32 m0, s90
	s_nop 0
	global_load_lds_dwordx4 v[240:241], off
	s_waitcnt vmcnt(8)
	s_waitcnt lgkmcnt(0)
	s_barrier
	s_setprio 1
	s_waitcnt lgkmcnt(0)
	v_mfma_f32_16x16x32_bf16 v[78:81], v[18:21], v[180:183], 0
	v_mfma_f32_16x16x32_bf16 v[74:77], v[34:37], v[180:183], 0
	v_mfma_f32_16x16x32_bf16 v[62:65], v[18:21], v[202:205], 0
	v_mfma_f32_16x16x32_bf16 v[58:61], v[34:37], v[202:205], 0
	v_mfma_f32_16x16x32_bf16 v[46:49], v[18:21], v[210:213], 0
	v_mfma_f32_16x16x32_bf16 v[42:45], v[34:37], v[210:213], 0
	v_mfma_f32_16x16x32_bf16 v[14:17], v[18:21], v[218:221], 0
	v_mfma_f32_16x16x32_bf16 v[10:13], v[34:37], v[218:221], 0
	v_mfma_f32_16x16x32_bf16 v[78:81], v[22:25], v[184:187], v[78:81]
	v_mfma_f32_16x16x32_bf16 v[74:77], v[38:41], v[184:187], v[74:77]
	v_mfma_f32_16x16x32_bf16 v[62:65], v[22:25], v[206:209], v[62:65]
	v_mfma_f32_16x16x32_bf16 v[58:61], v[38:41], v[206:209], v[58:61]
	v_mfma_f32_16x16x32_bf16 v[46:49], v[22:25], v[214:217], v[46:49]
	v_mfma_f32_16x16x32_bf16 v[42:45], v[38:41], v[214:217], v[42:45]
	v_mfma_f32_16x16x32_bf16 v[14:17], v[22:25], v[234:237], v[14:17]
	v_mfma_f32_16x16x32_bf16 v[10:13], v[38:41], v[234:237], v[10:13]
	s_setprio 0
	s_setprio 1
	v_mfma_f32_16x16x32_bf16 v[30:33], v[146:149], v[210:213], 0
	v_mfma_f32_16x16x32_bf16 v[26:29], v[172:175], v[210:213], 0
	v_mfma_f32_16x16x32_bf16 v[6:9], v[146:149], v[218:221], 0
	v_mfma_f32_16x16x32_bf16 v[2:5], v[172:175], v[218:221], 0
	v_mfma_f32_16x16x32_bf16 v[18:21], v[146:149], v[180:183], 0
	v_mfma_f32_16x16x32_bf16 v[22:25], v[172:175], v[180:183], 0
	v_mfma_f32_16x16x32_bf16 v[34:37], v[146:149], v[202:205], 0
	v_mfma_f32_16x16x32_bf16 v[38:41], v[172:175], v[202:205], 0
	v_mfma_f32_16x16x32_bf16 v[30:33], v[150:153], v[214:217], v[30:33]
	v_mfma_f32_16x16x32_bf16 v[26:29], v[176:179], v[214:217], v[26:29]
	v_mfma_f32_16x16x32_bf16 v[6:9], v[150:153], v[234:237], v[6:9]
	v_mfma_f32_16x16x32_bf16 v[2:5], v[176:179], v[234:237], v[2:5]
	v_mfma_f32_16x16x32_bf16 v[18:21], v[150:153], v[184:187], v[18:21]
	v_mfma_f32_16x16x32_bf16 v[22:25], v[176:179], v[184:187], v[22:25]
	v_mfma_f32_16x16x32_bf16 v[34:37], v[150:153], v[206:209], v[34:37]
	v_mfma_f32_16x16x32_bf16 v[38:41], v[176:179], v[206:209], v[38:41]
	s_setprio 0
	s_barrier
	s_add_i32 s19, 0, 0x18000
	v_add_u32_e32 v0, s19, v198
	s_add_i32 s20, 0, 0x1c000
	ds_read_b128 v[50:53], v0
	ds_read_b128 v[54:57], v0 offset:1024
	ds_read_b128 v[66:69], v0 offset:2048
	ds_read_b128 v[70:73], v0 offset:3072
	v_add_u32_e32 v0, s20, v198
	ds_read_b128 v[146:149], v0
	ds_read_b128 v[150:153], v0 offset:1024
	ds_read_b128 v[172:175], v0 offset:2048
	ds_read_b128 v[176:179], v0 offset:3072
	s_add_u32 s8, s8, 0x40000
	s_addc_u32 s9, s9, 0
	s_mov_b32 m0, s91
	v_lshl_add_u64 v[242:243], s[8:9], 0, v[154:155]
	ds_read_b128 v[180:183], v200 offset:32768
	ds_read_b128 v[184:187], v200 offset:33792
	ds_read_b128 v[202:205], v200 offset:34816
	ds_read_b128 v[206:209], v200 offset:35840
	ds_read_b128 v[210:213], v200 offset:36864
	ds_read_b128 v[214:217], v200 offset:37888
	ds_read_b128 v[218:221], v200 offset:38912
	ds_read_b128 v[234:237], v200 offset:39936
	global_load_lds_dwordx4 v[242:243], off
	v_lshl_add_u64 v[242:243], s[8:9], 0, v[158:159]
	s_mov_b32 m0, s76
	s_nop 0
	global_load_lds_dwordx4 v[242:243], off
	s_waitcnt vmcnt(8)
	s_waitcnt lgkmcnt(0)
	s_barrier
	s_setprio 1
	s_waitcnt lgkmcnt(0)
	v_mfma_f32_16x16x32_bf16 v[142:145], v[50:53], v[180:183], v[142:145]
	v_mfma_f32_16x16x32_bf16 v[138:141], v[66:69], v[180:183], v[138:141]
	v_mfma_f32_16x16x32_bf16 v[126:129], v[50:53], v[202:205], v[126:129]
	v_mfma_f32_16x16x32_bf16 v[122:125], v[66:69], v[202:205], v[122:125]
	v_mfma_f32_16x16x32_bf16 v[110:113], v[50:53], v[210:213], v[110:113]
	v_mfma_f32_16x16x32_bf16 v[106:109], v[66:69], v[210:213], v[106:109]
	v_mfma_f32_16x16x32_bf16 v[94:97], v[50:53], v[218:221], v[94:97]
	v_mfma_f32_16x16x32_bf16 v[90:93], v[66:69], v[218:221], v[90:93]
	v_mfma_f32_16x16x32_bf16 v[142:145], v[54:57], v[184:187], v[142:145]
	v_mfma_f32_16x16x32_bf16 v[138:141], v[70:73], v[184:187], v[138:141]
	v_mfma_f32_16x16x32_bf16 v[126:129], v[54:57], v[206:209], v[126:129]
	v_mfma_f32_16x16x32_bf16 v[122:125], v[70:73], v[206:209], v[122:125]
	v_mfma_f32_16x16x32_bf16 v[110:113], v[54:57], v[214:217], v[110:113]
	v_mfma_f32_16x16x32_bf16 v[106:109], v[70:73], v[214:217], v[106:109]
	v_mfma_f32_16x16x32_bf16 v[94:97], v[54:57], v[234:237], v[94:97]
	v_mfma_f32_16x16x32_bf16 v[90:93], v[70:73], v[234:237], v[90:93]
	s_setprio 0
	s_setprio 1
	v_mfma_f32_16x16x32_bf16 v[134:137], v[146:149], v[180:183], v[134:137]
	v_mfma_f32_16x16x32_bf16 v[130:133], v[172:175], v[180:183], v[130:133]
	v_mfma_f32_16x16x32_bf16 v[118:121], v[146:149], v[202:205], v[118:121]
	v_mfma_f32_16x16x32_bf16 v[114:117], v[172:175], v[202:205], v[114:117]
	v_mfma_f32_16x16x32_bf16 v[102:105], v[146:149], v[210:213], v[102:105]
	v_mfma_f32_16x16x32_bf16 v[98:101], v[172:175], v[210:213], v[98:101]
	v_mfma_f32_16x16x32_bf16 v[86:89], v[146:149], v[218:221], v[86:89]
	v_mfma_f32_16x16x32_bf16 v[82:85], v[172:175], v[218:221], v[82:85]
	v_mfma_f32_16x16x32_bf16 v[134:137], v[150:153], v[184:187], v[134:137]
	v_mfma_f32_16x16x32_bf16 v[130:133], v[176:179], v[184:187], v[130:133]
	v_mfma_f32_16x16x32_bf16 v[118:121], v[150:153], v[206:209], v[118:121]
	v_mfma_f32_16x16x32_bf16 v[114:117], v[176:179], v[206:209], v[114:117]
	v_mfma_f32_16x16x32_bf16 v[102:105], v[150:153], v[214:217], v[102:105]
	v_mfma_f32_16x16x32_bf16 v[98:101], v[176:179], v[214:217], v[98:101]
	v_mfma_f32_16x16x32_bf16 v[86:89], v[150:153], v[234:237], v[86:89]
	v_mfma_f32_16x16x32_bf16 v[82:85], v[176:179], v[234:237], v[82:85]
	s_setprio 0
	s_barrier
	s_add_i32 s8, s19, s69
	v_lshl_add_u64 v[188:189], v[188:189], 0, s[48:49]
	s_mov_b32 m0, s8
	ds_read_b128 v[180:183], v200 offset:49152
	ds_read_b128 v[184:187], v200 offset:50176
	ds_read_b128 v[202:205], v200 offset:51200
	ds_read_b128 v[206:209], v200 offset:52224
	ds_read_b128 v[210:213], v200 offset:53248
	ds_read_b128 v[214:217], v200 offset:54272
	ds_read_b128 v[218:221], v200 offset:55296
	ds_read_b128 v[234:237], v200 offset:56320
	global_load_lds_dwordx4 v[188:189], off
	s_add_i32 m0, s8, 0x2000
	s_add_u32 s6, s6, 0x40080
	v_lshl_add_u64 v[188:189], v[222:223], 0, s[48:49]
	s_addc_u32 s7, s7, 0
	s_add_i32 s8, s20, s69
	global_load_lds_dwordx4 v[188:189], off
	v_lshl_add_u64 v[188:189], s[6:7], 0, v[156:157]
	s_mov_b32 m0, s8
	s_nop 0
	global_load_lds_dwordx4 v[188:189], off
	v_lshl_add_u64 v[188:189], s[6:7], 0, v[160:161]
	s_add_i32 m0, s8, 0x2000
	s_nop 0
	global_load_lds_dwordx4 v[188:189], off
	v_lshl_add_u64 v[188:189], v[238:239], 0, s[48:49]
	s_mov_b32 m0, s77
	s_nop 0
	global_load_lds_dwordx4 v[188:189], off
	v_lshl_add_u64 v[188:189], v[240:241], 0, s[48:49]
	s_mov_b32 m0, s74
	s_nop 0
	global_load_lds_dwordx4 v[188:189], off
	s_waitcnt vmcnt(8)
	s_waitcnt lgkmcnt(0)
	s_barrier
	s_setprio 1
	s_waitcnt lgkmcnt(0)
	v_mfma_f32_16x16x32_bf16 v[78:81], v[50:53], v[180:183], v[78:81]
	v_mfma_f32_16x16x32_bf16 v[74:77], v[66:69], v[180:183], v[74:77]
	v_mfma_f32_16x16x32_bf16 v[62:65], v[50:53], v[202:205], v[62:65]
	v_mfma_f32_16x16x32_bf16 v[58:61], v[66:69], v[202:205], v[58:61]
	v_mfma_f32_16x16x32_bf16 v[46:49], v[50:53], v[210:213], v[46:49]
	v_mfma_f32_16x16x32_bf16 v[42:45], v[66:69], v[210:213], v[42:45]
	v_mfma_f32_16x16x32_bf16 v[14:17], v[50:53], v[218:221], v[14:17]
	v_mfma_f32_16x16x32_bf16 v[10:13], v[66:69], v[218:221], v[10:13]
	v_mfma_f32_16x16x32_bf16 v[78:81], v[54:57], v[184:187], v[78:81]
	v_mfma_f32_16x16x32_bf16 v[74:77], v[70:73], v[184:187], v[74:77]
	v_mfma_f32_16x16x32_bf16 v[62:65], v[54:57], v[206:209], v[62:65]
	v_mfma_f32_16x16x32_bf16 v[58:61], v[70:73], v[206:209], v[58:61]
	v_mfma_f32_16x16x32_bf16 v[46:49], v[54:57], v[214:217], v[46:49]
	v_mfma_f32_16x16x32_bf16 v[42:45], v[70:73], v[214:217], v[42:45]
	v_mfma_f32_16x16x32_bf16 v[14:17], v[54:57], v[234:237], v[14:17]
	v_mfma_f32_16x16x32_bf16 v[10:13], v[70:73], v[234:237], v[10:13]
	s_setprio 0
	s_setprio 1
	v_mfma_f32_16x16x32_bf16 v[18:21], v[146:149], v[180:183], v[18:21]
	v_mfma_f32_16x16x32_bf16 v[70:73], v[150:153], v[184:187], v[18:21]
	v_mfma_f32_16x16x32_bf16 v[18:21], v[172:175], v[180:183], v[22:25]
	v_mfma_f32_16x16x32_bf16 v[66:69], v[176:179], v[184:187], v[18:21]
	v_mfma_f32_16x16x32_bf16 v[18:21], v[146:149], v[202:205], v[34:37]
	v_mfma_f32_16x16x32_bf16 v[54:57], v[150:153], v[206:209], v[18:21]
	v_mfma_f32_16x16x32_bf16 v[18:21], v[172:175], v[202:205], v[38:41]
	v_mfma_f32_16x16x32_bf16 v[50:53], v[176:179], v[206:209], v[18:21]
	v_mfma_f32_16x16x32_bf16 v[18:21], v[146:149], v[210:213], v[30:33]
	v_mfma_f32_16x16x32_bf16 v[30:33], v[150:153], v[214:217], v[18:21]
	v_mfma_f32_16x16x32_bf16 v[18:21], v[172:175], v[210:213], v[26:29]
	v_mfma_f32_16x16x32_bf16 v[6:9], v[146:149], v[218:221], v[6:9]
	v_mfma_f32_16x16x32_bf16 v[2:5], v[172:175], v[218:221], v[2:5]
	v_mfma_f32_16x16x32_bf16 v[26:29], v[176:179], v[214:217], v[18:21]
	v_mfma_f32_16x16x32_bf16 v[6:9], v[150:153], v[234:237], v[6:9]
	v_mfma_f32_16x16x32_bf16 v[2:5], v[176:179], v[234:237], v[2:5]
	s_setprio 0
	s_barrier
	s_add_i32 s18, s18, 2
	s_add_u32 s0, s0, 0x100
	s_addc_u32 s1, s1, 0
	s_add_u32 s16, s16, 0x100
	s_addc_u32 s17, s17, 0
	s_cmp_gt_u32 s18, 13
	s_cbranch_scc0 .LBB0_745

.LBB0_1451:
	s_ashr_i32 s11, s10, 31
	s_lshl_b64 s[14:15], s[10:11], 19
	v_readlane_b32 s7, v253, 15
	s_add_u32 s14, s7, s14
	v_readlane_b32 s7, v253, 16
	s_addc_u32 s15, s7, s15
	s_and_b64 s[16:17], s[12:13], exec
	s_cselect_b32 s7, s15, s19
	s_cselect_b32 s11, s14, s18
	s_ashr_i32 s9, s8, 31
	s_lshl_b64 s[16:17], s[8:9], 19
	s_add_u32 s16, s40, s16
	s_addc_u32 s17, s41, s17
	s_and_b64 s[38:39], s[12:13], exec
	s_cselect_b32 s9, s17, s21
	s_cselect_b32 s70, s16, s20
	s_add_u32 s18, s18, 0x40080
	s_addc_u32 s19, s19, 0
	s_add_u32 s71, s20, 0x100
	s_addc_u32 s74, s21, 0
	s_mov_b32 s75, -2
	s_add_u32 s20, s18, 0xfffc0080
	s_addc_u32 s21, s19, -1
	s_add_i32 s76, 0, 0x10000
	s_cmp_eq_u32 s75, 12
	s_cselect_b32 s39, s7, s21
	s_cselect_b32 s38, s11, s20
	s_cselect_b32 s21, s9, s74
	s_cselect_b32 s20, s70, s71
	s_add_i32 s80, 0, 0x14000
	v_add_u32_e32 v142, s76, v235
	v_add_u32_e32 v158, s80, v235
	ds_read_b128 v[130:133], v142
	ds_read_b128 v[134:137], v142 offset:1024
	ds_read_b128 v[138:141], v142 offset:2048
	ds_read_b128 v[142:145], v142 offset:3072
	ds_read_b128 v[146:149], v158
	ds_read_b128 v[150:153], v158 offset:1024
	ds_read_b128 v[154:157], v158 offset:2048
	ds_read_b128 v[158:161], v158 offset:3072
	v_lshl_add_u64 v[214:215], s[18:19], 0, v[206:207]
	s_add_i32 m0, s42, 0xc000
	ds_read_b128 v[162:165], v237
	ds_read_b128 v[166:169], v237 offset:1024
	ds_read_b128 v[170:173], v237 offset:2048
	ds_read_b128 v[174:177], v237 offset:3072
	ds_read_b128 v[178:181], v237 offset:4096
	ds_read_b128 v[182:185], v237 offset:5120
	ds_read_b128 v[186:189], v237 offset:6144
	ds_read_b128 v[210:213], v237 offset:7168
	global_load_lds_dwordx4 v[214:215], off
	v_lshl_add_u64 v[214:215], s[18:19], 0, v[208:209]
	s_add_i32 m0, s42, 0xe000
	s_nop 0
	global_load_lds_dwordx4 v[214:215], off
	s_waitcnt vmcnt(8)
	s_waitcnt lgkmcnt(0)
	s_barrier
	s_setprio 1
	s_waitcnt lgkmcnt(0)
	v_mfma_f32_16x16x32_bf16 v[126:129], v[130:133], v[162:165], 0
	v_mfma_f32_16x16x32_bf16 v[122:125], v[138:141], v[162:165], 0
	v_mfma_f32_16x16x32_bf16 v[114:117], v[130:133], v[170:173], 0
	v_mfma_f32_16x16x32_bf16 v[106:109], v[138:141], v[170:173], 0
	v_mfma_f32_16x16x32_bf16 v[98:101], v[130:133], v[178:181], 0
	v_mfma_f32_16x16x32_bf16 v[90:93], v[138:141], v[178:181], 0
	v_mfma_f32_16x16x32_bf16 v[82:85], v[130:133], v[186:189], 0
	v_mfma_f32_16x16x32_bf16 v[74:77], v[138:141], v[186:189], 0
	v_mfma_f32_16x16x32_bf16 v[126:129], v[134:137], v[166:169], v[126:129]
	v_mfma_f32_16x16x32_bf16 v[122:125], v[142:145], v[166:169], v[122:125]
	v_mfma_f32_16x16x32_bf16 v[114:117], v[134:137], v[174:177], v[114:117]
	v_mfma_f32_16x16x32_bf16 v[106:109], v[142:145], v[174:177], v[106:109]
	v_mfma_f32_16x16x32_bf16 v[98:101], v[134:137], v[182:185], v[98:101]
	v_mfma_f32_16x16x32_bf16 v[90:93], v[142:145], v[182:185], v[90:93]
	v_mfma_f32_16x16x32_bf16 v[82:85], v[134:137], v[210:213], v[82:85]
	v_mfma_f32_16x16x32_bf16 v[74:77], v[142:145], v[210:213], v[74:77]
	s_setprio 0
	s_setprio 1
	v_mfma_f32_16x16x32_bf16 v[118:121], v[146:149], v[162:165], 0
	v_mfma_f32_16x16x32_bf16 v[110:113], v[154:157], v[162:165], 0
	v_mfma_f32_16x16x32_bf16 v[102:105], v[146:149], v[170:173], 0
	v_mfma_f32_16x16x32_bf16 v[94:97], v[154:157], v[170:173], 0
	v_mfma_f32_16x16x32_bf16 v[86:89], v[146:149], v[178:181], 0
	v_mfma_f32_16x16x32_bf16 v[78:81], v[154:157], v[178:181], 0
	v_mfma_f32_16x16x32_bf16 v[70:73], v[146:149], v[186:189], 0
	v_mfma_f32_16x16x32_bf16 v[66:69], v[154:157], v[186:189], 0
	v_mfma_f32_16x16x32_bf16 v[118:121], v[150:153], v[166:169], v[118:121]
	v_mfma_f32_16x16x32_bf16 v[110:113], v[158:161], v[166:169], v[110:113]
	v_mfma_f32_16x16x32_bf16 v[102:105], v[150:153], v[174:177], v[102:105]
	v_mfma_f32_16x16x32_bf16 v[94:97], v[158:161], v[174:177], v[94:97]
	v_mfma_f32_16x16x32_bf16 v[86:89], v[150:153], v[182:185], v[86:89]
	v_mfma_f32_16x16x32_bf16 v[78:81], v[158:161], v[182:185], v[78:81]
	v_mfma_f32_16x16x32_bf16 v[70:73], v[150:153], v[210:213], v[70:73]
	v_mfma_f32_16x16x32_bf16 v[66:69], v[158:161], v[210:213], v[66:69]
	s_setprio 0
	s_barrier
	s_add_i32 s76, s76, s25
	v_lshl_add_u64 v[214:215], s[20:21], 0, v[200:201]
	s_mov_b32 m0, s76
	ds_read_b128 v[162:165], v237 offset:16384
	ds_read_b128 v[166:169], v237 offset:17408
	ds_read_b128 v[170:173], v237 offset:18432
	ds_read_b128 v[174:177], v237 offset:19456
	ds_read_b128 v[178:181], v237 offset:20480
	ds_read_b128 v[182:185], v237 offset:21504
	ds_read_b128 v[186:189], v237 offset:22528
	ds_read_b128 v[210:213], v237 offset:23552
	global_load_lds_dwordx4 v[214:215], off
	s_add_i32 m0, s76, 0x2000
	s_add_u32 s76, s20, 0x40000
	v_lshl_add_u64 v[216:217], s[20:21], 0, v[204:205]
	s_addc_u32 s77, s21, 0
	s_add_i32 s80, s80, s25
	global_load_lds_dwordx4 v[216:217], off
	v_lshl_add_u64 v[218:219], s[76:77], 0, v[200:201]
	s_mov_b32 m0, s80
	v_lshl_add_u64 v[220:221], s[38:39], 0, v[202:203]
	global_load_lds_dwordx4 v[218:219], off
	v_lshl_add_u64 v[218:219], s[76:77], 0, v[204:205]
	s_add_i32 m0, s80, 0x2000
	s_nop 0
	global_load_lds_dwordx4 v[218:219], off
	v_lshl_add_u64 v[218:219], s[38:39], 0, v[198:199]
	s_mov_b32 m0, s42
	s_nop 0
	global_load_lds_dwordx4 v[218:219], off
	s_mov_b32 m0, s43
	s_nop 0
	global_load_lds_dwordx4 v[220:221], off
	s_waitcnt vmcnt(8)
	s_waitcnt lgkmcnt(0)
	s_barrier
	s_setprio 1
	s_waitcnt lgkmcnt(0)
	v_mfma_f32_16x16x32_bf16 v[62:65], v[130:133], v[162:165], 0
	v_mfma_f32_16x16x32_bf16 v[58:61], v[138:141], v[162:165], 0
	v_mfma_f32_16x16x32_bf16 v[50:53], v[130:133], v[170:173], 0
	v_mfma_f32_16x16x32_bf16 v[42:45], v[138:141], v[170:173], 0
	v_mfma_f32_16x16x32_bf16 v[34:37], v[130:133], v[178:181], 0
	v_mfma_f32_16x16x32_bf16 v[26:29], v[138:141], v[178:181], 0
	v_mfma_f32_16x16x32_bf16 v[18:21], v[130:133], v[186:189], 0
	v_mfma_f32_16x16x32_bf16 v[10:13], v[138:141], v[186:189], 0
	v_mfma_f32_16x16x32_bf16 v[62:65], v[134:137], v[166:169], v[62:65]
	v_mfma_f32_16x16x32_bf16 v[58:61], v[142:145], v[166:169], v[58:61]
	v_mfma_f32_16x16x32_bf16 v[50:53], v[134:137], v[174:177], v[50:53]
	v_mfma_f32_16x16x32_bf16 v[42:45], v[142:145], v[174:177], v[42:45]
	v_mfma_f32_16x16x32_bf16 v[34:37], v[134:137], v[182:185], v[34:37]
	v_mfma_f32_16x16x32_bf16 v[26:29], v[142:145], v[182:185], v[26:29]
	v_mfma_f32_16x16x32_bf16 v[18:21], v[134:137], v[210:213], v[18:21]
	v_mfma_f32_16x16x32_bf16 v[10:13], v[142:145], v[210:213], v[10:13]
	s_setprio 0
	s_setprio 1
	v_mfma_f32_16x16x32_bf16 v[54:57], v[146:149], v[162:165], 0
	v_mfma_f32_16x16x32_bf16 v[46:49], v[154:157], v[162:165], 0
	v_mfma_f32_16x16x32_bf16 v[38:41], v[146:149], v[170:173], 0
	v_mfma_f32_16x16x32_bf16 v[30:33], v[154:157], v[170:173], 0
	v_mfma_f32_16x16x32_bf16 v[22:25], v[146:149], v[178:181], 0
	v_mfma_f32_16x16x32_bf16 v[14:17], v[154:157], v[178:181], 0
	v_mfma_f32_16x16x32_bf16 v[6:9], v[146:149], v[186:189], 0
	v_mfma_f32_16x16x32_bf16 v[2:5], v[154:157], v[186:189], 0
	v_mfma_f32_16x16x32_bf16 v[54:57], v[150:153], v[166:169], v[54:57]
	v_mfma_f32_16x16x32_bf16 v[46:49], v[158:161], v[166:169], v[46:49]
	v_mfma_f32_16x16x32_bf16 v[38:41], v[150:153], v[174:177], v[38:41]
	v_mfma_f32_16x16x32_bf16 v[30:33], v[158:161], v[174:177], v[30:33]
	v_mfma_f32_16x16x32_bf16 v[22:25], v[150:153], v[182:185], v[22:25]
	v_mfma_f32_16x16x32_bf16 v[14:17], v[158:161], v[182:185], v[14:17]
	v_mfma_f32_16x16x32_bf16 v[6:9], v[150:153], v[210:213], v[6:9]
	v_mfma_f32_16x16x32_bf16 v[2:5], v[158:161], v[210:213], v[2:5]
	s_setprio 0
	s_barrier
	s_add_i32 s76, 0, 0x18000
	s_add_i32 s77, 0, 0x1c000
	v_add_u32_e32 v142, s76, v235
	v_add_u32_e32 v158, s77, v235
	ds_read_b128 v[130:133], v142
	ds_read_b128 v[134:137], v142 offset:1024
	ds_read_b128 v[138:141], v142 offset:2048
	ds_read_b128 v[142:145], v142 offset:3072
	ds_read_b128 v[146:149], v158
	ds_read_b128 v[150:153], v158 offset:1024
	ds_read_b128 v[154:157], v158 offset:2048
	ds_read_b128 v[158:161], v158 offset:3072
	s_add_u32 s38, s38, 0x40000
	s_addc_u32 s39, s39, 0
	s_mov_b32 m0, s44
	v_lshl_add_u64 v[222:223], s[38:39], 0, v[198:199]
	ds_read_b128 v[162:165], v237 offset:32768
	ds_read_b128 v[166:169], v237 offset:33792
	ds_read_b128 v[170:173], v237 offset:34816
	ds_read_b128 v[174:177], v237 offset:35840
	ds_read_b128 v[178:181], v237 offset:36864
	ds_read_b128 v[182:185], v237 offset:37888
	ds_read_b128 v[186:189], v237 offset:38912
	ds_read_b128 v[210:213], v237 offset:39936
	global_load_lds_dwordx4 v[222:223], off
	v_lshl_add_u64 v[222:223], s[38:39], 0, v[202:203]
	s_mov_b32 m0, s45
	s_nop 0
	global_load_lds_dwordx4 v[222:223], off
	s_waitcnt vmcnt(8)
	s_waitcnt lgkmcnt(0)
	s_barrier
	s_setprio 1
	s_waitcnt lgkmcnt(0)
	v_mfma_f32_16x16x32_bf16 v[126:129], v[130:133], v[162:165], v[126:129]
	v_mfma_f32_16x16x32_bf16 v[122:125], v[138:141], v[162:165], v[122:125]
	v_mfma_f32_16x16x32_bf16 v[114:117], v[130:133], v[170:173], v[114:117]
	v_mfma_f32_16x16x32_bf16 v[106:109], v[138:141], v[170:173], v[106:109]
	v_mfma_f32_16x16x32_bf16 v[98:101], v[130:133], v[178:181], v[98:101]
	v_mfma_f32_16x16x32_bf16 v[90:93], v[138:141], v[178:181], v[90:93]
	v_mfma_f32_16x16x32_bf16 v[82:85], v[130:133], v[186:189], v[82:85]
	v_mfma_f32_16x16x32_bf16 v[74:77], v[138:141], v[186:189], v[74:77]
	v_mfma_f32_16x16x32_bf16 v[126:129], v[134:137], v[166:169], v[126:129]
	v_mfma_f32_16x16x32_bf16 v[122:125], v[142:145], v[166:169], v[122:125]
	v_mfma_f32_16x16x32_bf16 v[114:117], v[134:137], v[174:177], v[114:117]
	v_mfma_f32_16x16x32_bf16 v[106:109], v[142:145], v[174:177], v[106:109]
	v_mfma_f32_16x16x32_bf16 v[98:101], v[134:137], v[182:185], v[98:101]
	v_mfma_f32_16x16x32_bf16 v[90:93], v[142:145], v[182:185], v[90:93]
	v_mfma_f32_16x16x32_bf16 v[82:85], v[134:137], v[210:213], v[82:85]
	v_mfma_f32_16x16x32_bf16 v[74:77], v[142:145], v[210:213], v[74:77]
	s_setprio 0
	s_setprio 1
	v_mfma_f32_16x16x32_bf16 v[118:121], v[146:149], v[162:165], v[118:121]
	v_mfma_f32_16x16x32_bf16 v[110:113], v[154:157], v[162:165], v[110:113]
	v_mfma_f32_16x16x32_bf16 v[102:105], v[146:149], v[170:173], v[102:105]
	v_mfma_f32_16x16x32_bf16 v[94:97], v[154:157], v[170:173], v[94:97]
	v_mfma_f32_16x16x32_bf16 v[86:89], v[146:149], v[178:181], v[86:89]
	v_mfma_f32_16x16x32_bf16 v[78:81], v[154:157], v[178:181], v[78:81]
	v_mfma_f32_16x16x32_bf16 v[70:73], v[146:149], v[186:189], v[70:73]
	v_mfma_f32_16x16x32_bf16 v[66:69], v[154:157], v[186:189], v[66:69]
	v_mfma_f32_16x16x32_bf16 v[118:121], v[150:153], v[166:169], v[118:121]
	v_mfma_f32_16x16x32_bf16 v[110:113], v[158:161], v[166:169], v[110:113]
	v_mfma_f32_16x16x32_bf16 v[102:105], v[150:153], v[174:177], v[102:105]
	v_mfma_f32_16x16x32_bf16 v[94:97], v[158:161], v[174:177], v[94:97]
	v_mfma_f32_16x16x32_bf16 v[86:89], v[150:153], v[182:185], v[86:89]
	v_mfma_f32_16x16x32_bf16 v[78:81], v[158:161], v[182:185], v[78:81]
	v_mfma_f32_16x16x32_bf16 v[70:73], v[150:153], v[210:213], v[70:73]
	v_mfma_f32_16x16x32_bf16 v[66:69], v[158:161], v[210:213], v[66:69]
	s_setprio 0
	s_barrier
	s_add_i32 s38, s76, s25
	v_lshl_add_u64 v[214:215], v[214:215], 0, s[48:49]
	s_mov_b32 m0, s38
	ds_read_b128 v[162:165], v237 offset:49152
	ds_read_b128 v[166:169], v237 offset:50176
	ds_read_b128 v[170:173], v237 offset:51200
	ds_read_b128 v[174:177], v237 offset:52224
	ds_read_b128 v[178:181], v237 offset:53248
	ds_read_b128 v[182:185], v237 offset:54272
	ds_read_b128 v[186:189], v237 offset:55296
	ds_read_b128 v[210:213], v237 offset:56320
	global_load_lds_dwordx4 v[214:215], off
	s_add_i32 m0, s38, 0x2000
	s_add_u32 s20, s20, 0x40080
	v_lshl_add_u64 v[214:215], v[216:217], 0, s[48:49]
	s_addc_u32 s21, s21, 0
	s_add_i32 s38, s77, s25
	global_load_lds_dwordx4 v[214:215], off
	v_lshl_add_u64 v[214:215], s[20:21], 0, v[200:201]
	s_mov_b32 m0, s38
	s_nop 0
	global_load_lds_dwordx4 v[214:215], off
	v_lshl_add_u64 v[214:215], s[20:21], 0, v[204:205]
	s_add_i32 m0, s38, 0x2000
	s_nop 0
	global_load_lds_dwordx4 v[214:215], off
	v_lshl_add_u64 v[214:215], v[218:219], 0, s[48:49]
	s_mov_b32 m0, s46
	s_nop 0
	global_load_lds_dwordx4 v[214:215], off
	v_lshl_add_u64 v[214:215], v[220:221], 0, s[48:49]
	s_mov_b32 m0, s47
	s_nop 0
	global_load_lds_dwordx4 v[214:215], off
	s_waitcnt vmcnt(8)
	s_waitcnt lgkmcnt(0)
	s_barrier
	s_setprio 1
	s_waitcnt lgkmcnt(0)
	v_mfma_f32_16x16x32_bf16 v[62:65], v[130:133], v[162:165], v[62:65]
	v_mfma_f32_16x16x32_bf16 v[58:61], v[138:141], v[162:165], v[58:61]
	v_mfma_f32_16x16x32_bf16 v[50:53], v[130:133], v[170:173], v[50:53]
	v_mfma_f32_16x16x32_bf16 v[42:45], v[138:141], v[170:173], v[42:45]
	v_mfma_f32_16x16x32_bf16 v[34:37], v[130:133], v[178:181], v[34:37]
	v_mfma_f32_16x16x32_bf16 v[26:29], v[138:141], v[178:181], v[26:29]
	v_mfma_f32_16x16x32_bf16 v[18:21], v[130:133], v[186:189], v[18:21]
	v_mfma_f32_16x16x32_bf16 v[10:13], v[138:141], v[186:189], v[10:13]
	v_mfma_f32_16x16x32_bf16 v[62:65], v[134:137], v[166:169], v[62:65]
	v_mfma_f32_16x16x32_bf16 v[58:61], v[142:145], v[166:169], v[58:61]
	v_mfma_f32_16x16x32_bf16 v[50:53], v[134:137], v[174:177], v[50:53]
	v_mfma_f32_16x16x32_bf16 v[42:45], v[142:145], v[174:177], v[42:45]
	v_mfma_f32_16x16x32_bf16 v[34:37], v[134:137], v[182:185], v[34:37]
	v_mfma_f32_16x16x32_bf16 v[26:29], v[142:145], v[182:185], v[26:29]
	v_mfma_f32_16x16x32_bf16 v[18:21], v[134:137], v[210:213], v[18:21]
	v_mfma_f32_16x16x32_bf16 v[10:13], v[142:145], v[210:213], v[10:13]
	s_setprio 0
	s_setprio 1
	v_mfma_f32_16x16x32_bf16 v[54:57], v[146:149], v[162:165], v[54:57]
	v_mfma_f32_16x16x32_bf16 v[46:49], v[154:157], v[162:165], v[46:49]
	v_mfma_f32_16x16x32_bf16 v[38:41], v[146:149], v[170:173], v[38:41]
	v_mfma_f32_16x16x32_bf16 v[30:33], v[154:157], v[170:173], v[30:33]
	v_mfma_f32_16x16x32_bf16 v[22:25], v[146:149], v[178:181], v[22:25]
	v_mfma_f32_16x16x32_bf16 v[14:17], v[154:157], v[178:181], v[14:17]
	v_mfma_f32_16x16x32_bf16 v[6:9], v[146:149], v[186:189], v[6:9]
	v_mfma_f32_16x16x32_bf16 v[2:5], v[154:157], v[186:189], v[2:5]
	v_mfma_f32_16x16x32_bf16 v[54:57], v[150:153], v[166:169], v[54:57]
	v_mfma_f32_16x16x32_bf16 v[46:49], v[158:161], v[166:169], v[46:49]
	v_mfma_f32_16x16x32_bf16 v[38:41], v[150:153], v[174:177], v[38:41]
	v_mfma_f32_16x16x32_bf16 v[30:33], v[158:161], v[174:177], v[30:33]
	v_mfma_f32_16x16x32_bf16 v[22:25], v[150:153], v[182:185], v[22:25]
	v_mfma_f32_16x16x32_bf16 v[14:17], v[158:161], v[182:185], v[14:17]
	v_mfma_f32_16x16x32_bf16 v[6:9], v[150:153], v[210:213], v[6:9]
	v_mfma_f32_16x16x32_bf16 v[2:5], v[158:161], v[210:213], v[2:5]
	s_setprio 0
	s_barrier
	s_add_i32 s75, s75, 2
	s_add_u32 s18, s18, 0x100
	s_addc_u32 s19, s19, 0
	s_add_u32 s71, s71, 0x100
	s_addc_u32 s74, s74, 0
	s_cmp_gt_u32 s75, 13
	s_cbranch_scc0 .LBB0_1452
